# gm spatial-gating loop: also prefetch the next iteration's f32 spatial-weight tiles into spare VGPRs during the previous epilogue
# speedup vs baseline: 1.0026x; 1.0016x over previous
; #define LAS __attribute__((address_space(3)))
; DI void gm_unit(const Ctx& cx, const bf16_t* __restrict__ PG, bf16_t* __restrict__ Ogm, const float* __restrict__ gvn, const float* __restrict__ ws, const float* __restrict__ bs, int unit, LAS unsigned char* lds) {
;     ...
;   const int tb = wi & 3, dbp = wi >> 2;
;   const int i16 = lane & 15, q4l = i16 >> 2, p4 = i16 & 3, gp = (lane >> 4) & 1;
;   LAS unsigned char* trb = lds + (8 * h + q4l) * 320 + (16 * gp + 4 * p4) * 2;
;   const int t = tb * 32 + r;
;   const int chn = tid & 15, srow = tid >> 4;
;   for (int gi = 0; gi < 4; ++gi) {
;     const int g = gh * 4 + gi;
;     u32x4 vraw[4];
; #pragma unroll
;     for (int it = 0; it < 4; ++it) vraw[it] = *(const u32x4*)(PG + (size_t)(tok0 + srow + 32 * it) * PGW + 4096 + g * 128 + chn * 8);
;     const f32x4 g0 = *(const f32x4*)(gvn + g * 128 + chn * 8), g1 = *(const f32x4*)(gvn + g * 128 + chn * 8 + 4);
;     const float* wrow = ws + ((size_t)g * 128 + t) * 128 + 8 * h;
;     f32x4 wv[8][2];
; #pragma unroll
;     for (int ks = 0; ks < 8; ++ks) if (ks < 4 || tb >= 2) { wv[ks][0] = *(const f32x4*)(wrow + ks * 16); wv[ks][1] = *(const f32x4*)(wrow + ks * 16 + 4); }
;     const bf16_t* up_ = PG + (size_t)(tok0 + t) * PGW + 3072 + g * 128;
;     u32x2 uu[2][4];
; #pragma unroll
;     for (int e = 0; e < 2; ++e)
; #pragma unroll
;       for (int qd = 0; qd < 4; ++qd) uu[e][qd] = *(const u32x2*)(up_ + (2 * dbp + e) * 32 + 8 * qd + 4 * h);
;     const float bias = bs[g * 128 + t];
.LBB0_915:
	s_or_b64 exec, exec, s[22:23]
	v_add_u32_e32 v0, s24, v88
	v_mad_i64_i32 v[102:103], s[22:23], v0, s33, v[96:97]
	v_add_u32_e32 v0, s24, v140
	v_mad_i64_i32 v[104:105], s[22:23], v0, s33, v[96:97]
	v_add_u32_e32 v0, s24, v141
	v_mad_i64_i32 v[106:107], s[22:23], v0, s33, v[96:97]
	v_add_u32_e32 v0, s24, v142
	s_bfe_u32 s36, s10, 0x10002
	v_mad_i64_i32 v[108:109], s[22:23], v0, s33, v[96:97]
	s_lshl_b32 s22, s36, 11
	s_mov_b32 s23, s13
	s_bfe_u32 s37, s25, 0x20006
	s_lshl_b32 s12, s36, 10
	v_lshl_add_u64 v[110:111], v[100:101], 0, s[22:23]
	s_ashr_i32 s23, s25, 8
	s_lshl_b32 s25, s37, 5
	s_cmp_gt_u32 s37, 1
	s_cselect_b64 s[38:39], -1, 0
	s_add_i32 s24, s25, s24
	s_lshl_b32 s22, s23, 6
	v_add_u32_e32 v0, s24, v216
	s_waitcnt lgkmcnt(0)
	v_ashrrev_i32_e32 v1, 31, v0
	v_or_b32_e32 v4, s22, v178
	s_lshl_b32 s41, s23, 7
	s_ashr_i32 s23, s22, 31
	v_lshlrev_b64 v[2:3], 11, v[0:1]
	v_ashrrev_i32_e32 v5, 31, v4
	v_lshl_or_b32 v1, s36, 18, v143
	v_lshl_add_u64 v[2:3], v[4:5], 1, v[2:3]
	v_lshl_or_b32 v208, s37, 14, v1
	v_lshl_or_b32 v1, s36, 9, v216
	s_lshl_b64 s[22:23], s[22:23], 1
	v_lshl_add_u64 v[112:113], s[0:1], 0, v[2:3]
	v_or_b32_e32 v1, s25, v1
	v_mov_b64_e32 v[2:3], s[22:23]
	v_lshl_add_u64 v[114:115], v[94:95], 0, v[208:209]
	v_lshlrev_b32_e32 v208, 2, v1
	v_mad_i64_i32 v[0:1], s[22:23], v0, s33, v[2:3]
	v_lshl_add_u64 v[116:117], s[30:31], 0, v[208:209]
	v_lshl_add_u64 v[118:119], v[98:99], 0, v[0:1]
	s_mov_b64 s[24:25], 0
	v_add_u32_e32 v145, s41, v138
	v_lshl_add_u64 v[204:205], v[102:103], 0, s[12:13]
	global_load_dwordx4 v[180:183], v[204:205], off
	v_lshl_add_u64 v[204:205], v[104:105], 0, s[12:13]
	global_load_dwordx4 v[184:187], v[204:205], off
	v_lshl_add_u64 v[204:205], v[106:107], 0, s[12:13]
	global_load_dwordx4 v[188:191], v[204:205], off
	v_lshl_add_u64 v[204:205], v[108:109], 0, s[12:13]
	global_load_dwordx4 v[192:195], v[204:205], off
	global_load_dwordx4 v[196:199], v[110:111], off
	global_load_dwordx4 v[200:203], v[110:111], off offset:-16
	v_lshl_add_u64 v[204:205], v[114:115], 0, s[24:25]
	global_load_dwordx4 v[152:155], v[204:205], off offset:16
	global_load_dwordx4 v[156:159], v[204:205], off
	global_load_dwordx4 v[160:163], v[204:205], off offset:80
	global_load_dwordx4 v[168:171], v[204:205], off offset:64
	global_load_dwordx4 v[172:175], v[204:205], off offset:144
	global_load_dwordx4 v[210:213], v[204:205], off offset:128
	global_load_dwordx4 v[224:227], v[204:205], off offset:208
	global_load_dwordx2 v[206:207], v[204:205], off offset:192
	global_load_dwordx2 v[214:215], v[204:205], off offset:200
	s_barrier
	s_branch .LBB0_917
.LBB0_916:
	s_waitcnt vmcnt(8)
	v_lshlrev_b32_e32 v64, 16, v134
	s_waitcnt vmcnt(0)
	s_cmp_lg_u32 s24, 0x30000
	s_cbranch_scc0 .Lgm_nopf
	v_lshl_add_u64 v[204:205], v[102:103], 0, s[28:29]
	v_lshl_add_u64 v[204:205], v[204:205], 0, s[12:13]
	global_load_dwordx4 v[180:183], v[204:205], off
	v_lshl_add_u64 v[204:205], v[104:105], 0, s[28:29]
	v_lshl_add_u64 v[204:205], v[204:205], 0, s[12:13]
	global_load_dwordx4 v[184:187], v[204:205], off
	v_lshl_add_u64 v[204:205], v[106:107], 0, s[28:29]
	v_lshl_add_u64 v[204:205], v[204:205], 0, s[12:13]
	global_load_dwordx4 v[188:191], v[204:205], off
	v_lshl_add_u64 v[204:205], v[108:109], 0, s[28:29]
	v_lshl_add_u64 v[204:205], v[204:205], 0, s[12:13]
	global_load_dwordx4 v[192:195], v[204:205], off
	v_lshl_add_u64 v[204:205], v[110:111], 0, s[96:97]
	global_load_dwordx4 v[196:199], v[204:205], off
	global_load_dwordx4 v[200:203], v[204:205], off offset:-16
	s_add_u32 s98, s24, 0x10000
	s_addc_u32 s99, s25, 0
	v_lshl_add_u64 v[204:205], v[114:115], 0, s[98:99]
	global_load_dwordx4 v[152:155], v[204:205], off offset:16
	global_load_dwordx4 v[156:159], v[204:205], off
	global_load_dwordx4 v[160:163], v[204:205], off offset:80
	global_load_dwordx4 v[168:171], v[204:205], off offset:64
	global_load_dwordx4 v[172:175], v[204:205], off offset:144
	global_load_dwordx4 v[210:213], v[204:205], off offset:128
	global_load_dwordx4 v[224:227], v[204:205], off offset:208
	global_load_dwordx2 v[206:207], v[204:205], off offset:192
	global_load_dwordx2 v[214:215], v[204:205], off offset:200

; DI void gm_unit(const Ctx& cx, const bf16_t* __restrict__ PG, bf16_t* __restrict__ Ogm, const float* __restrict__ gvn, const float* __restrict__ ws, const float* __restrict__ bs, int unit, LAS unsigned char* lds) {
;     ...
;     const float* wrow = ws + ((size_t)g * 128 + t) * 128 + 8 * h;
;     f32x4 wv[8][2];
; #pragma unroll
;     for (int ks = 0; ks < 8; ++ks) if (ks < 4 || tb >= 2) { wv[ks][0] = *(const f32x4*)(wrow + ks * 16); wv[ks][1] = *(const f32x4*)(wrow + ks * 16 + 4); }
.LBB0_917:
	v_lshl_add_u64 v[120:121], v[114:115], 0, s[24:25]
	s_nop 0
	v_cndmask_b32_e64 v122, 0, 1, s[38:39]
	v_cmp_ne_u32_e64 s[36:37], 1, v122
	s_andn2_b64 vcc, exec, s[38:39]
	s_cbranch_vccz .LBB0_926
	s_and_b64 vcc, exec, s[36:37]
	s_cbranch_vccz .LBB0_927

; #define LAS __attribute__((address_space(3)))
; DI unsigned cvt_pk_bf16(float lo, float hi) { unsigned r; asm volatile("v_cvt_pk_bf16_f32 %0, %1, %2" : "=v"(r) : "v"(lo), "v"(hi)); return r; }
; DI float bf_lo(unsigned w) { return __uint_as_float(w << 16); }
; DI float bf_hi(unsigned w) { return __uint_as_float(w & 0xffff0000u); }
; DI void gm_unit(const Ctx& cx, const bf16_t* __restrict__ PG, bf16_t* __restrict__ Ogm, const float* __restrict__ gvn, const float* __restrict__ ws, const float* __restrict__ bs, int unit, LAS unsigned char* lds) {
;     ...
;       for (int qd = 0; qd < 4; ++qd) uu[e][qd] = *(const u32x2*)(up_ + (2 * dbp + e) * 32 + 8 * qd + 4 * h);
;     const float bias = bs[g * 128 + t];
; #pragma unroll
;     for (int it = 0; it < 4; ++it) { const int s = srow + 32 * it; const u32x4 w = vraw[it]; const float ri = rinv[s];
;       u32x4 o;
;       o.x = cvt_pk_bf16(bf_lo(w.x) * ri * g0.x, bf_hi(w.x) * ri * g0.y);
;       o.y = cvt_pk_bf16(bf_lo(w.y) * ri * g0.z, bf_hi(w.y) * ri * g0.w);
;       o.z = cvt_pk_bf16(bf_lo(w.z) * ri * g1.x, bf_hi(w.z) * ri * g1.y);
;       o.w = cvt_pk_bf16(bf_lo(w.w) * ri * g1.z, bf_hi(w.w) * ri * g1.w);
;       *(LAS u32x4*)(lds + s * 320 + chn * 16) = o; }
;     __syncthreads();
.LBB0_922:
	v_lshl_add_u64 v[120:121], v[118:119], 0, s[12:13]
	global_load_dwordx2 v[134:135], v[120:121], off offset:-64
	global_load_dwordx2 v[132:133], v[120:121], off offset:-48
	global_load_dwordx2 v[130:131], v[120:121], off offset:-32
	global_load_dwordx2 v[128:129], v[120:121], off offset:-16
	ds_read_b32 v147, v139 offset:49152
	s_waitcnt vmcnt(4)
	v_mov_b32_e32 v28, v180
	v_mov_b32_e32 v29, v181
	v_mov_b32_e32 v30, v182
	v_mov_b32_e32 v31, v183
	v_mov_b32_e32 v24, v184
	v_mov_b32_e32 v25, v185
	v_mov_b32_e32 v26, v186
	v_mov_b32_e32 v27, v187
	v_mov_b32_e32 v20, v188
	v_mov_b32_e32 v21, v189
	v_mov_b32_e32 v22, v190
	v_mov_b32_e32 v23, v191
	v_mov_b32_e32 v12, v192
	v_mov_b32_e32 v13, v193
	v_mov_b32_e32 v14, v194
	v_mov_b32_e32 v15, v195
	v_mov_b32_e32 v8, v196
	v_mov_b32_e32 v9, v197
	v_mov_b32_e32 v10, v198
	v_mov_b32_e32 v11, v199
	v_mov_b32_e32 v16, v200
	v_mov_b32_e32 v17, v201
	v_mov_b32_e32 v18, v202
	v_mov_b32_e32 v19, v203
	v_lshlrev_b32_e32 v148, 16, v28
	v_and_b32_e32 v28, 0xffff0000, v28
	global_load_dwordx2 v[126:127], v[120:121], off
	global_load_dwordx2 v[124:125], v[120:121], off offset:16
	global_load_dwordx2 v[122:123], v[120:121], off offset:32
	s_nop 0
	global_load_dwordx2 v[120:121], v[120:121], off offset:48
	s_nop 0
	global_load_dword v146, v[116:117], off
	s_and_b64 vcc, exec, s[36:37]
	s_waitcnt lgkmcnt(0)
	v_mul_f32_e32 v148, v147, v148
	v_mul_f32_e32 v28, v147, v28
	s_waitcnt vmcnt(17)
	v_mul_f32_e32 v148, v16, v148
	v_mul_f32_e32 v28, v17, v28
	v_cvt_pk_bf16_f32 v28, v148, v28
	v_lshlrev_b32_e32 v148, 16, v29
	v_and_b32_e32 v29, 0xffff0000, v29
	v_mul_f32_e32 v148, v147, v148
	v_mul_f32_e32 v29, v147, v29
	v_mul_f32_e32 v148, v18, v148
	v_mul_f32_e32 v29, v19, v29
	v_cvt_pk_bf16_f32 v29, v148, v29
	v_lshlrev_b32_e32 v148, 16, v30
	v_and_b32_e32 v30, 0xffff0000, v30
	v_mul_f32_e32 v148, v147, v148
	v_mul_f32_e32 v30, v147, v30
	v_mul_f32_e32 v148, v8, v148
	v_mul_f32_e32 v30, v9, v30
	v_cvt_pk_bf16_f32 v30, v148, v30
	v_lshlrev_b32_e32 v148, 16, v31
	v_and_b32_e32 v31, 0xffff0000, v31
	v_mul_f32_e32 v31, v147, v31
	v_mul_f32_e32 v148, v147, v148
	v_mul_f32_e32 v31, v11, v31
	v_mul_f32_e32 v148, v10, v148
	v_cvt_pk_bf16_f32 v31, v148, v31
	ds_write_b128 v144, v[28:31]
	ds_read_b32 v28, v139 offset:49280
	v_lshlrev_b32_e32 v29, 16, v24
	v_and_b32_e32 v24, 0xffff0000, v24
	s_waitcnt lgkmcnt(0)
	v_mul_f32_e32 v29, v28, v29
	v_mul_f32_e32 v24, v28, v24
	v_mul_f32_e32 v29, v16, v29
	v_mul_f32_e32 v24, v17, v24
	v_cvt_pk_bf16_f32 v24, v29, v24
	v_lshlrev_b32_e32 v29, 16, v25
	v_and_b32_e32 v25, 0xffff0000, v25
	v_mul_f32_e32 v29, v28, v29
	v_mul_f32_e32 v25, v28, v25
	v_mul_f32_e32 v29, v18, v29
	v_mul_f32_e32 v25, v19, v25
	v_cvt_pk_bf16_f32 v25, v29, v25
	v_lshlrev_b32_e32 v29, 16, v26
	v_and_b32_e32 v26, 0xffff0000, v26
	v_mul_f32_e32 v29, v28, v29
	v_mul_f32_e32 v26, v28, v26
	v_mul_f32_e32 v29, v8, v29
	v_mul_f32_e32 v26, v9, v26
	v_cvt_pk_bf16_f32 v26, v29, v26
	v_lshlrev_b32_e32 v29, 16, v27
	v_and_b32_e32 v27, 0xffff0000, v27
	v_mul_f32_e32 v27, v28, v27
	v_mul_f32_e32 v29, v28, v29
	v_mul_f32_e32 v27, v11, v27
	v_mul_f32_e32 v29, v10, v29
	v_cvt_pk_bf16_f32 v27, v29, v27
	ds_write_b128 v144, v[24:27] offset:10240
	ds_read_b32 v24, v139 offset:49408
	v_lshlrev_b32_e32 v25, 16, v20
	v_and_b32_e32 v20, 0xffff0000, v20
	s_waitcnt lgkmcnt(0)
	v_mul_f32_e32 v25, v24, v25
	v_mul_f32_e32 v20, v24, v20
	v_mul_f32_e32 v25, v16, v25
	v_mul_f32_e32 v20, v17, v20
	v_cvt_pk_bf16_f32 v20, v25, v20
	v_lshlrev_b32_e32 v25, 16, v21
	v_and_b32_e32 v21, 0xffff0000, v21
	v_mul_f32_e32 v25, v24, v25
	v_mul_f32_e32 v21, v24, v21
	v_mul_f32_e32 v25, v18, v25
	v_mul_f32_e32 v21, v19, v21
	v_cvt_pk_bf16_f32 v21, v25, v21
	v_lshlrev_b32_e32 v25, 16, v22
	v_and_b32_e32 v22, 0xffff0000, v22
	v_mul_f32_e32 v25, v24, v25
	v_mul_f32_e32 v22, v24, v22
	v_mul_f32_e32 v25, v8, v25
	v_mul_f32_e32 v22, v9, v22
	v_cvt_pk_bf16_f32 v22, v25, v22
	v_lshlrev_b32_e32 v25, 16, v23
	v_and_b32_e32 v23, 0xffff0000, v23
	v_mul_f32_e32 v23, v24, v23
	v_mul_f32_e32 v25, v24, v25
	v_mul_f32_e32 v23, v11, v23
	v_mul_f32_e32 v25, v10, v25
	v_cvt_pk_bf16_f32 v23, v25, v23
	ds_write_b128 v144, v[20:23] offset:20480
	ds_read_b32 v20, v139 offset:49536
	v_lshlrev_b32_e32 v21, 16, v12
	v_and_b32_e32 v12, 0xffff0000, v12
	s_waitcnt lgkmcnt(0)
	v_mul_f32_e32 v21, v20, v21
	v_mul_f32_e32 v12, v20, v12
	v_mul_f32_e32 v16, v16, v21
	v_mul_f32_e32 v12, v17, v12
	v_cvt_pk_bf16_f32 v12, v16, v12
	v_lshlrev_b32_e32 v16, 16, v13
	v_and_b32_e32 v13, 0xffff0000, v13
	v_mul_f32_e32 v16, v20, v16
	v_mul_f32_e32 v13, v20, v13
	v_mul_f32_e32 v16, v18, v16
	v_mul_f32_e32 v13, v19, v13
	v_cvt_pk_bf16_f32 v13, v16, v13
	v_lshlrev_b32_e32 v16, 16, v14
	v_and_b32_e32 v14, 0xffff0000, v14
	v_mul_f32_e32 v16, v20, v16
	v_mul_f32_e32 v14, v20, v14
	v_mul_f32_e32 v8, v8, v16
	v_mul_f32_e32 v9, v9, v14
	v_cvt_pk_bf16_f32 v14, v8, v9
	v_lshlrev_b32_e32 v8, 16, v15
	v_and_b32_e32 v9, 0xffff0000, v15
	v_mul_f32_e32 v8, v20, v8
	v_mul_f32_e32 v9, v20, v9
	v_mul_f32_e32 v8, v10, v8
	v_mul_f32_e32 v9, v11, v9
	v_cvt_pk_bf16_f32 v15, v8, v9
	ds_write_b128 v144, v[12:15] offset:30720
	s_waitcnt lgkmcnt(0)
	s_barrier
; #define MFMA32(a, b, c) __builtin_amdgcn_mfma_f32_32x32x16_bf16((a), (b), (c), 0, 0, 0)
; DI void gm_unit(const Ctx& cx, const bf16_t* __restrict__ PG, bf16_t* __restrict__ Ogm, const float* __restrict__ gvn, const float* __restrict__ ws, const float* __restrict__ bs, int unit, LAS unsigned char* lds) {
;     ...
;     for (int ks = 0; ks < 8; ++ks) if (ks < 4 || tb >= 2) {
;       const bf16x8 bfrag = pack8(wv[ks][0].x, wv[ks][0].y, wv[ks][0].z, wv[ks][0].w, wv[ks][1].x, wv[ks][1].y, wv[ks][1].z, wv[ks][1].w);
; #pragma unroll
;       for (int e = 0; e < 2; ++e) { const int db = 2 * dbp + e;
;         const bf16x8 af = tr_pair(trb + (16 * ks) * 320 + db * 64, trb + (16 * ks + 4) * 320 + db * 64);
;         acc[e] = MFMA32(af, bfrag, acc[e]); }
;     }
	s_waitcnt vmcnt(15)
	v_cvt_pk_bf16_f32 v4, v156, v157
	v_cvt_pk_bf16_f32 v5, v158, v159
	v_cvt_pk_bf16_f32 v6, v152, v153
	v_cvt_pk_bf16_f32 v7, v154, v155
	ds_read_b64_tr_b16 v[0:1], v145
	ds_read_b64_tr_b16 v[2:3], v145 offset:1280
	ds_read_b64_tr_b16 v[10:11], v145 offset:1344
	ds_read_b64_tr_b16 v[8:9], v145 offset:64
	s_waitcnt lgkmcnt(2)
	v_mfma_f32_32x32x16_bf16 v[16:31], v[0:3], v[4:7], 0
	s_waitcnt vmcnt(13)
	v_cvt_pk_bf16_f32 v84, v168, v169
	v_cvt_pk_bf16_f32 v85, v170, v171
	v_cvt_pk_bf16_f32 v86, v160, v161
	v_cvt_pk_bf16_f32 v87, v162, v163
	ds_read_b64_tr_b16 v[80:81], v145 offset:5120
	ds_read_b64_tr_b16 v[82:83], v145 offset:6400
	ds_read_b64_tr_b16 v[150:151], v145 offset:6464
	ds_read_b64_tr_b16 v[148:149], v145 offset:5184
	s_waitcnt vmcnt(11)
	v_cvt_pk_bf16_f32 v76, v210, v211
	v_cvt_pk_bf16_f32 v77, v212, v213
	s_waitcnt lgkmcnt(4)
	v_mfma_f32_32x32x16_bf16 v[0:15], v[8:11], v[4:7], 0
	v_cvt_pk_bf16_f32 v78, v172, v173
	v_cvt_pk_bf16_f32 v79, v174, v175
	s_waitcnt lgkmcnt(2)
	v_mfma_f32_32x32x16_bf16 v[16:31], v[80:83], v[84:87], v[16:31]
	ds_read_b64_tr_b16 v[72:73], v145 offset:10240
	ds_read_b64_tr_b16 v[74:75], v145 offset:11520
	ds_read_b64_tr_b16 v[82:83], v145 offset:11584
	ds_read_b64_tr_b16 v[80:81], v145 offset:10304
	s_waitcnt vmcnt(9)
	v_cvt_pk_bf16_f32 v68, v206, v207
	v_cvt_pk_bf16_f32 v69, v214, v215
	v_cvt_pk_bf16_f32 v70, v224, v225
	v_cvt_pk_bf16_f32 v71, v226, v227
	s_waitcnt lgkmcnt(4)
	v_mfma_f32_32x32x16_bf16 v[0:15], v[148:151], v[84:87], v[0:15]
	s_waitcnt lgkmcnt(2)
	v_mfma_f32_32x32x16_bf16 v[16:31], v[72:75], v[76:79], v[16:31]
	ds_read_b64_tr_b16 v[64:65], v145 offset:15360
	ds_read_b64_tr_b16 v[66:67], v145 offset:16640
	ds_read_b64_tr_b16 v[74:75], v145 offset:16704
	ds_read_b64_tr_b16 v[72:73], v145 offset:15424
	s_waitcnt lgkmcnt(4)
	v_mfma_f32_32x32x16_bf16 v[0:15], v[80:83], v[76:79], v[0:15]
	s_waitcnt lgkmcnt(2)
	v_mfma_f32_32x32x16_bf16 v[16:31], v[64:67], v[68:71], v[16:31]
	s_waitcnt lgkmcnt(0)
	v_mfma_f32_32x32x16_bf16 v[0:15], v[72:75], v[68:71], v[0:15]
	s_cbranch_vccz .LBB0_929
	s_and_b64 vcc, exec, s[36:37]
	s_cbranch_vccz .LBB0_930
